# v56 + GEMM tile-loop headers: group size is always 8, generic signed division replaced by a shift
# baseline (speedup 1.0000x reference)
;     __device__ bool next(int i, Unit& u) const {
;         const long L = (long)i * G + c; if (L >= nwg) return false;
;         int wgid = (int)L; { const int q = nwg / NXCD, r = nwg % NXCD, xcd = wgid % NXCD, off = wgid / NXCD; wgid = (xcd < r ? xcd * (q + 1) : r * (q + 1) + (xcd - r) * q) + off; }
;         const int nig = WGM * nN, gid = wgid / nig, fm = gid * WGM, gsz = (nM - fm) < WGM ? (nM - fm) : WGM;
;         u.pm = fm + ((wgid % nig) % gsz); u.pn = (wgid % nig) / gsz; return true;
;     }
.LBB0_338:
	s_add_i32 s31, s31, 1
	s_mul_i32 s0, s31, s95
	s_mul_hi_u32 s1, s31, s94
	s_add_i32 s1, s1, s0
	s_mul_i32 s0, s31, s94
	s_add_u32 s0, s0, s22
	s_addc_u32 s1, s1, s24
	v_mov_b64_e32 v[2:3], 0xc80
	v_cmp_lt_i64_e64 s[6:7], s[0:1], v[2:3]
	v_mov_b64_e32 v[2:3], 0xc7f
	v_cmp_gt_i64_e32 vcc, s[0:1], v[2:3]
	s_cbranch_vccnz .LBB0_340
	s_ashr_i32 s1, s0, 31
	s_lshr_b32 s1, s1, 29
	s_add_i32 s1, s0, s1
	s_ashr_i32 s14, s1, 3
	s_and_b32 s1, s1, -8
	s_sub_i32 s0, s0, s1
	s_cmp_lt_i32 s0, 0
	s_movk_i32 s1, 0x191
	s_cselect_b32 s1, s1, 0x190
	s_mul_i32 s0, s1, s0
	s_add_i32 s0, s0, s14
	s_mul_hi_i32 s1, s0, 0x51eb851f
	s_lshr_b32 s14, s1, 31
	s_ashr_i32 s1, s1, 6
	s_add_i32 s1, s1, s14
	s_lshl_b32 s14, s1, 3
	s_sub_i32 s15, 0x80, s14
	s_min_i32 s15, s15, 8
	s_mulk_i32 s1, 0xc8
	s_sub_i32 s0, s0, s1
	s_ashr_i32 s34, s0, 3
	s_mul_i32 s1, s34, s15
	s_sub_i32 s0, s0, s1
	s_add_i32 s35, s0, s14

;     __device__ bool next(int i, Unit& u) const {
;         const long L = (long)i * G + c; if (L >= nwg) return false;
;         int wgid = (int)L; { const int q = nwg / NXCD, r = nwg % NXCD, xcd = wgid % NXCD, off = wgid / NXCD; wgid = (xcd < r ? xcd * (q + 1) : r * (q + 1) + (xcd - r) * q) + off; }
;         const int nig = WGM * nN, gid = wgid / nig, fm = gid * WGM, gsz = (nM - fm) < WGM ? (nM - fm) : WGM;
;         u.pm = fm + ((wgid % nig) % gsz); u.pn = (wgid % nig) / gsz; return true;
;     }
.LBB0_572:
	s_ashr_i32 s6, s12, 3
	s_add_i32 s6, s17, s6
	s_ashr_i32 s7, s6, 31
	s_lshr_b32 s7, s7, 27
	s_add_i32 s7, s6, s7
	s_ashr_i32 s12, s7, 5
	s_lshl_b32 s12, s12, 3
	s_sub_i32 s13, 0x80, s12
	s_min_i32 s13, s13, 8
	s_andn2_b32 s7, s7, 31
	s_sub_i32 s6, s6, s7
	s_ashr_i32 s34, s6, 3
	s_mul_i32 s7, s34, s13
	s_sub_i32 s6, s6, s7
	s_add_i32 s35, s12, s6

;     __device__ bool next(int i, Unit& u) const {
;         const long L = (long)i * G + c; if (L >= nwg) return false;
;         int wgid = (int)L; { const int q = nwg / NXCD, r = nwg % NXCD, xcd = wgid % NXCD, off = wgid / NXCD; wgid = (xcd < r ? xcd * (q + 1) : r * (q + 1) + (xcd - r) * q) + off; }
;         const int nig = WGM * nN, gid = wgid / nig, fm = gid * WGM, gsz = (nM - fm) < WGM ? (nM - fm) : WGM;
;         u.pm = fm + ((wgid % nig) % gsz); u.pn = (wgid % nig) / gsz; return true;
;     }
.LBB0_662:
	s_add_i32 s29, s29, 1
	s_mul_i32 s0, s29, s95
	s_mul_hi_u32 s1, s29, s94
	s_add_i32 s1, s1, s0
	s_mul_i32 s0, s29, s94
	s_add_u32 s0, s0, s20
	s_addc_u32 s1, s1, s22
	v_mov_b64_e32 v[2:3], 0x600
	v_cmp_lt_i64_e64 s[4:5], s[0:1], v[2:3]
	v_mov_b64_e32 v[2:3], 0x5ff
	v_cmp_gt_i64_e32 vcc, s[0:1], v[2:3]
	s_cbranch_vccnz .LBB0_664
	s_ashr_i32 s1, s0, 31
	s_lshr_b32 s1, s1, 29
	s_add_i32 s1, s0, s1
	s_ashr_i32 s10, s1, 3
	s_and_b32 s1, s1, -8
	s_sub_i32 s0, s0, s1
	s_cmp_lt_i32 s0, 0
	s_movk_i32 s1, 0xc1
	s_cselect_b32 s1, s1, 0xc0
	s_mul_i32 s0, s1, s0
	s_add_i32 s0, s0, s10
	s_mul_hi_i32 s1, s0, 0x2aaaaaab
	s_lshr_b32 s10, s1, 31
	s_ashr_i32 s1, s1, 4
	s_add_i32 s1, s1, s10
	s_lshl_b32 s10, s1, 3
	s_sub_i32 s11, 0x80, s10
	s_min_i32 s11, s11, 8
	s_mulk_i32 s1, 0x60
	s_sub_i32 s0, s0, s1
	s_ashr_i32 s30, s0, 3
	s_mul_i32 s1, s30, s11
	s_sub_i32 s0, s0, s1
	s_add_i32 s31, s0, s10

;     __device__ bool next(int i, Unit& u) const {
;         const long L = (long)i * G + c; if (L >= nwg) return false;
;         int wgid = (int)L; { const int q = nwg / NXCD, r = nwg % NXCD, xcd = wgid % NXCD, off = wgid / NXCD; wgid = (xcd < r ? xcd * (q + 1) : r * (q + 1) + (xcd - r) * q) + off; }
;         const int nig = WGM * nN, gid = wgid / nig, fm = gid * WGM, gsz = (nM - fm) < WGM ? (nM - fm) : WGM;
;         u.pm = fm + ((wgid % nig) % gsz); u.pn = (wgid % nig) / gsz; return true;
;     }
.LBB0_831:
	s_ashr_i32 s0, s10, 3
	s_add_i32 s0, s16, s0
	s_ashr_i32 s1, s0, 31
	s_lshr_b32 s1, s1, 27
	s_add_i32 s1, s0, s1
	s_ashr_i32 s10, s1, 5
	s_lshl_b32 s10, s10, 3
	s_sub_i32 s11, 0x80, s10
	s_min_i32 s11, s11, 8
	s_andn2_b32 s1, s1, 31
	s_sub_i32 s0, s0, s1
	s_ashr_i32 s30, s0, 3
	s_mul_i32 s1, s30, s11
	s_sub_i32 s0, s0, s1
	s_add_i32 s31, s10, s0

;     __device__ bool next(int i, Unit& u) const {
;         const long L = (long)i * G + c; if (L >= nwg) return false;
;         int wgid = (int)L; { const int q = nwg / NXCD, r = nwg % NXCD, xcd = wgid % NXCD, off = wgid / NXCD; wgid = (xcd < r ? xcd * (q + 1) : r * (q + 1) + (xcd - r) * q) + off; }
;         const int nig = WGM * nN, gid = wgid / nig, fm = gid * WGM, gsz = (nM - fm) < WGM ? (nM - fm) : WGM;
;         u.pm = fm + ((wgid % nig) % gsz); u.pn = (wgid % nig) / gsz; return true;
;     }
.LBB0_1043:
	s_add_i32 s29, s29, 1
	s_mul_i32 s0, s29, s95
	s_mul_hi_u32 s1, s29, s94
	s_add_i32 s1, s1, s0
	s_mul_i32 s0, s29, s94
	s_add_u32 s4, s0, s20
	s_addc_u32 s5, s1, s22
	v_cmp_gt_i64_e32 vcc, s[4:5], v[150:151]
	v_cmp_lt_i64_e64 s[0:1], s[4:5], v[148:149]
	s_cbranch_vccnz .LBB0_1045
	s_ashr_i32 s5, s4, 31
	s_lshr_b32 s5, s5, 29
	s_add_i32 s5, s4, s5
	s_ashr_i32 s10, s5, 3
	s_and_b32 s5, s5, -8
	s_sub_i32 s4, s4, s5
	s_cmp_lt_i32 s4, 0
	s_movk_i32 s5, 0x161
	s_cselect_b32 s5, s5, 0x160
	s_mul_i32 s4, s5, s4
	s_add_i32 s4, s4, s10
	s_mul_hi_i32 s5, s4, 0x2e8ba2e9
	s_lshr_b32 s10, s5, 31
	s_ashr_i32 s5, s5, 5
	s_add_i32 s5, s5, s10
	s_lshl_b32 s10, s5, 3
	s_sub_i32 s11, 0x80, s10
	s_min_i32 s11, s11, 8
	s_mulk_i32 s5, 0xb0
	s_sub_i32 s4, s4, s5
	s_ashr_i32 s30, s4, 3
	s_mul_i32 s5, s30, s11
	s_sub_i32 s4, s4, s5
	s_add_i32 s31, s4, s10

;     __device__ bool next(int i, Unit& u) const {
;         const long L = (long)i * G + c; if (L >= nwg) return false;
;         int wgid = (int)L; { const int q = nwg / NXCD, r = nwg % NXCD, xcd = wgid % NXCD, off = wgid / NXCD; wgid = (xcd < r ? xcd * (q + 1) : r * (q + 1) + (xcd - r) * q) + off; }
;         const int nig = WGM * nN, gid = wgid / nig, fm = gid * WGM, gsz = (nM - fm) < WGM ? (nM - fm) : WGM;
;         u.pm = fm + ((wgid % nig) % gsz); u.pn = (wgid % nig) / gsz; return true;
;     }
.LBB0_1137:
	s_ashr_i32 s0, s12, 3
	s_add_i32 s0, s18, s0
	s_ashr_i32 s1, s0, 31
	s_lshr_b32 s1, s1, 27
	s_add_i32 s1, s0, s1
	s_ashr_i32 s12, s1, 5
	s_lshl_b32 s12, s12, 3
	s_sub_i32 s13, 0x80, s12
	s_min_i32 s13, s13, 8
	s_andn2_b32 s1, s1, 31
	s_sub_i32 s0, s0, s1
	s_ashr_i32 s34, s0, 3
	s_mul_i32 s1, s34, s13
	s_sub_i32 s0, s0, s1
	s_add_i32 s35, s12, s0
